# v14 + panel barriers: returning arrive lets the last arriver skip polling; ticket loop: wave 0 no longer blocks on the prefetched ticket
# speedup vs baseline: 1.0046x; 1.0046x over previous
; __device__ __forceinline__ unsigned xb_ld(unsigned* p)              { return __hip_atomic_load(p, __ATOMIC_RELAXED, __HIP_MEMORY_SCOPE_AGENT); }
; __device__ __forceinline__ unsigned xb_add(unsigned* p, unsigned v) { return __hip_atomic_fetch_add(p, v, __ATOMIC_RELAXED, __HIP_MEMORY_SCOPE_AGENT); }
; #define XB_SPIN(cond, bar) do { unsigned _sp = 0; while (cond) { __builtin_amdgcn_s_sleep(1); \
;     if ((++_sp & 255u) == 0u) { if (xb_ld(&(bar)[XB_TMO])) break; if (_sp > XB_SPIN_CAP) { atomicAdd(&(bar)[XB_TMO], 1u); break; } } } } while (0)
; __device__ __forceinline__ void xcd_barrier(const XcdBarrier& b) {
;     asm volatile("s_waitcnt vmcnt(0)" ::: "memory");
;     __syncthreads();
;     if (threadIdx.x == 0) {
;         unsigned* bar = b.bar;
;         __builtin_amdgcn_s_waitcnt(0);
;         unsigned nloc = b.st[0], nx = b.st[1];
;         if (nloc == 0u) { xcd_barrier_complete(bar, b.x, nloc, nx); b.st[0] = nloc; b.st[1] = nx; }
;         const unsigned old = xb_add(&bar[XB_XSUB(b.x)], 1u);
;         const unsigned gen = old / nloc;
;         if (old + 1u == (gen + 1u) * nloc) {
;             __builtin_amdgcn_fence(__ATOMIC_RELEASE, "agent");
;             asm volatile("s_waitcnt vmcnt(0)" ::: "memory");
;             const unsigned og = xb_add(&bar[XB_TOP], 1u);
;             const unsigned tg = og / nx;
;             if (og + 1u == (tg + 1u) * nx) xb_add(&bar[XB_TOPGEN], 1u);
;             else XB_SPIN(xb_ld(&bar[XB_TOPGEN]) == tg, bar);
;             __builtin_amdgcn_fence(__ATOMIC_ACQUIRE, "agent");
;             xb_add(&bar[XB_XGEN(b.x)], 1u);
;             asm volatile("s_waitcnt vmcnt(0)" ::: "memory");
;         } else {
;             XB_SPIN(xb_ld(&bar[XB_XGEN(b.x)]) == gen, bar);
;             __builtin_amdgcn_fence(__ATOMIC_ACQUIRE, "agent");
;             asm volatile("s_waitcnt vmcnt(0)" ::: "memory");
;         }
;     }
;     __syncthreads();
; }
.Lpc1_fast:
	s_and_b32 s98, s2, 7
	s_lshl_b32 s98, s98, 2
	s_bfe_u32 s99, s2, 0x20003
	s_or_b32 s98, s98, s99
	s_lshl_b32 s98, s98, 6
	s_add_i32 s98, s98, 0xa400
	v_mov_b32_e32 v250, s98
	v_mov_b32_e32 v252, 1
	global_atomic_add v251, v250, v252, s[54:55] offset:16 sc0
	s_mov_b32 s99, 0
	s_waitcnt vmcnt(0)
	v_readfirstlane_b32 s98, v251
	s_cmp_ge_u32 s98, 7
	s_cbranch_scc1 .Lpc1_ok

; template <bool REMAP = false>
; __device__ __forceinline__ void transpose_convert(LAS unsigned char* lds, const float* src, bf16_t* dst, int K, int N, int G, int bid) {
;     ...
;     if (bid < ntiles) { const int k0 = (bid / ntn) * 128, n0 = (bid % ntn) * 64;
; #pragma unroll
;         for (int i = 0; i < 4; ++i) v[i] = __builtin_nontemporal_load((const f32x4*)(src + (size_t)(k0 + r0 + 32 * i) * N + n0 + c4 * 4)); }
;     for (int t = bid; t < ntiles; t += G) {
;         const int k0 = (t / ntn) * 128, n0 = (t % ntn) * 64;
;         asm volatile("s_waitcnt lgkmcnt(0)" ::: "memory"); __builtin_amdgcn_s_barrier(); asm volatile("" ::: "memory");
; #pragma unroll
;         for (int i = 0; i < 4; ++i) {
; #pragma unroll
;             for (int j = 0; j < 4; ++j) tile[(r0 + 32 * i) * 65 + c4 * 4 + j] = v[i][j]; }
;         asm volatile("s_waitcnt lgkmcnt(0)" ::: "memory"); __builtin_amdgcn_s_barrier(); asm volatile("" ::: "memory");
;         if (t + G < ntiles) { const int k1 = ((t + G) / ntn) * 128, n1 = ((t + G) % ntn) * 64;
; #pragma unroll
;             for (int i = 0; i < 4; ++i) v[i] = __builtin_nontemporal_load((const f32x4*)(src + (size_t)(k1 + r0 + 32 * i) * N + n1 + c4 * 4)); }
.Ldyn7_nofetch:
	s_or_b64 exec, exec, s[18:19]
	s_waitcnt lgkmcnt(0)
	s_barrier
	ds_read_b32 v1, v46
	s_waitcnt lgkmcnt(0)
	v_readfirstlane_b32 s99, v1
	s_nop 3
	s_cmp_gt_u32 s99, 0x1ff
	s_cbranch_scc1 .Ldyn7_exit
	s_cmpk_lt_i32 s99, 0x200
	s_cselect_b64 s[4:5], -1, 0
	s_cmpk_gt_i32 s99, 0xff
	v_lshl_add_u32 v20, v214, 2, 0
	s_cbranch_scc1 .Ldyn7_call2pre
	s_add_u32 s6, s44, 0x1000000
	s_addc_u32 s7, s45, 0
	s_ashr_i32 s8, s99, 31
	s_lshr_b32 s8, s8, 27
	s_add_i32 s8, s99, s8
	s_lshl_b32 s9, s8, 2
	s_and_b32 s8, s8, 0x3ffffe0
	s_sub_i32 s8, s99, s8
	s_and_b32 s9, s9, 0xffffff80
	s_lshl_b32 s8, s8, 6
	s_waitcnt vmcnt(1)
	v_or_b32_e32 v8, s9, v214
	s_ashr_i32 s9, s8, 31
	s_lshl_b64 s[8:9], s[8:9], 2
	v_and_b32_e32 v24, 15, v164
	s_add_u32 s8, s6, s8
	s_addc_u32 s9, s7, s9
	v_lshlrev_b32_e32 v18, 4, v24
	v_mov_b32_e32 v19, 0
	v_ashrrev_i32_e32 v9, 31, v8
	v_lshl_add_u64 v[10:11], s[8:9], 0, v[18:19]
	v_lshlrev_b64 v[0:1], 13, v[8:9]
	v_lshl_add_u64 v[12:13], v[10:11], 0, v[0:1]
	s_mov_b32 s10, 0x40000
	v_or_b32_e32 v8, 64, v8
	v_add_co_u32_e32 v14, vcc, s10, v12
	v_ashrrev_i32_e32 v9, 31, v8
	s_nop 0
	v_addc_co_u32_e32 v15, vcc, 0, v13, vcc
	v_lshlrev_b64 v[8:9], 13, v[8:9]
	s_mov_b32 s11, 0xc0000
	v_lshl_add_u64 v[16:17], v[10:11], 0, v[8:9]
	v_add_co_u32_e32 v22, vcc, s11, v12
	global_load_dwordx4 v[0:3], v[12:13], off nt
	global_load_dwordx4 v[4:7], v[14:15], off nt
	v_addc_co_u32_e32 v23, vcc, 0, v13, vcc
	global_load_dwordx4 v[8:11], v[16:17], off nt
	global_load_dwordx4 v[12:15], v[22:23], off nt
	v_add_u32_e32 v21, 0x200, v164
	v_add_u32_e32 v22, 0, v18
	v_lshrrev_b32_e32 v21, 4, v21
	v_mul_u32_u24_e32 v23, 0x104, v214
	v_lshl_add_u32 v27, v21, 2, 0
	v_mul_u32_u24_e32 v28, 0x820, v24
	v_add_u32_e32 v22, v22, v23
	v_lshl_add_u64 v[16:17], s[6:7], 0, v[18:19]
	v_lshl_add_u64 v[18:19], s[24:25], 0, v[18:19]
	s_lshl_b32 s17, s99, 6
	s_lshl_b32 s16, s98, 6
	v_add_u32_e32 v23, 0x2080, v22
	v_add_u32_e32 v24, 0x2088, v22
	v_add_u32_e32 v25, 0x4100, v22
	v_add_u32_e32 v26, v20, v28
	v_add_u32_e32 v27, v27, v28
	v_add_u32_e32 v28, 0x4108, v22
	v_add_u32_e32 v29, 0x6180, v22
	s_mov_b32 s18, s99
	s_branch .LBB0_625

; __device__ __forceinline__ unsigned xb_ld(unsigned* p)              { return __hip_atomic_load(p, __ATOMIC_RELAXED, __HIP_MEMORY_SCOPE_AGENT); }
; __device__ __forceinline__ unsigned xb_add(unsigned* p, unsigned v) { return __hip_atomic_fetch_add(p, v, __ATOMIC_RELAXED, __HIP_MEMORY_SCOPE_AGENT); }
; #define XB_SPIN(cond, bar) do { unsigned _sp = 0; while (cond) { __builtin_amdgcn_s_sleep(1); \
;     if ((++_sp & 255u) == 0u) { if (xb_ld(&(bar)[XB_TMO])) break; if (_sp > XB_SPIN_CAP) { atomicAdd(&(bar)[XB_TMO], 1u); break; } } } } while (0)
; __device__ __forceinline__ void xcd_barrier(const XcdBarrier& b) {
;     asm volatile("s_waitcnt vmcnt(0)" ::: "memory");
;     __syncthreads();
;     if (threadIdx.x == 0) {
;         unsigned* bar = b.bar;
;         __builtin_amdgcn_s_waitcnt(0);
;         unsigned nloc = b.st[0], nx = b.st[1];
;         if (nloc == 0u) { xcd_barrier_complete(bar, b.x, nloc, nx); b.st[0] = nloc; b.st[1] = nx; }
;         const unsigned old = xb_add(&bar[XB_XSUB(b.x)], 1u);
;         const unsigned gen = old / nloc;
;         if (old + 1u == (gen + 1u) * nloc) {
;             __builtin_amdgcn_fence(__ATOMIC_RELEASE, "agent");
;             asm volatile("s_waitcnt vmcnt(0)" ::: "memory");
;             const unsigned og = xb_add(&bar[XB_TOP], 1u);
;             const unsigned tg = og / nx;
;             if (og + 1u == (tg + 1u) * nx) xb_add(&bar[XB_TOPGEN], 1u);
;             else XB_SPIN(xb_ld(&bar[XB_TOPGEN]) == tg, bar);
;             __builtin_amdgcn_fence(__ATOMIC_ACQUIRE, "agent");
;             xb_add(&bar[XB_XGEN(b.x)], 1u);
;             asm volatile("s_waitcnt vmcnt(0)" ::: "memory");
;         } else {
;             XB_SPIN(xb_ld(&bar[XB_XGEN(b.x)]) == gen, bar);
;             __builtin_amdgcn_fence(__ATOMIC_ACQUIRE, "agent");
;             asm volatile("s_waitcnt vmcnt(0)" ::: "memory");
;         }
;     }
;     __syncthreads();
; }
.Lpb8_fast:
	global_atomic_add v251, v250, v252, s[54:55] offset:4 sc0
	v_mov_b32_e32 v253, 0xa100
	global_atomic_add v253, v252, s[54:55]
	s_mov_b32 s99, 0
	s_waitcnt vmcnt(0)
	v_readfirstlane_b32 s98, v251
	s_cmp_ge_u32 s98, 7
	s_cbranch_scc1 .Lpw8_ok
